# attnA K/V tiles staged by LDS-DMA into two per-wave LDS buffers, two tiles in flight (was one register-staged tile)
# speedup vs baseline: 1.1062x; 1.0021x over previous
; #define LAS __attribute__((address_space(3)))
; __device__ __forceinline__ int tidx() { int t = threadIdx.x; asm volatile("" : "+v"(t)); return t; }
; __device__ __forceinline__ void attnA_unit(const Args& a, int unit, LAS unsigned char* lds) {
;     const int tid = tidx(), wid = __builtin_amdgcn_readfirstlane(tid >> 6), lane = tid & 63, ql = lane & 31, h = lane >> 5;
;     const int b = unit / 24, rem = unit % 24, hh = rem >> 2, blk = rem & 3;
;     const bf16_t* P = (const bf16_t*)(a.ws + WS_P);
;     bf16_t* OA = (bf16_t*)(a.ws + OFF_OA); float* LSE = (float*)(a.ws + OFF_LSE); bf16_t* MIX = (bf16_t*)(a.ws + WS_MIX);
;     LAS unsigned char* wl = lds + wid * 8192;
;     const unsigned char* kbase = (const unsigned char*)(P + (size_t)b * SEQ * PW + 384 + 64 * hh);
;     const unsigned char* vbase = (const unsigned char*)(P + (size_t)b * SEQ * PW + 768 + 64 * hh);
; #pragma unroll 1
;     for (int pidx = 0; pidx < 3; ++pidx) {
;         const int dl = (pidx == 0) ? 1 : (pidx == 1 ? 4 : 16), Ls = SEQ / dl;
;         if (pidx == 2) { __syncthreads(); }
; #pragma unroll 1
;         for (int e = 0; e < 2; ++e) {
;             const int qt = 2 * wid + e, r = qt % dl, i0 = (512 * blk) / dl + 32 * (qt / dl);
;             const int tq = dl * (i0 + ql) + r;
;             bf16x8 qf[4];
;             { const bf16_t* qp = P + ((size_t)b * SEQ + tq) * PW + 64 * hh + 8 * h;
; #pragma unroll
;               for (int s = 0; s < 4; ++s) qf[s] = *(const bf16x8*)(qp + 16 * s); }
;             f32x16 o0, o1;
; #pragma unroll
;             for (int i = 0; i < 16; ++i) { o0[i] = 0.f; o1[i] = 0.f; }
;             float m = -1e30f, l = 0.f;
;             int kt0 = 0, kt1 = 4;
;             if (i0 - 64 < 0) kt0 = (i0 - 32 < 0) ? 2 : 1;
;             if (i0 + 64 >= Ls) kt1 = (i0 + 32 >= Ls) ? 2 : 3;
;             const unsigned pitch = (unsigned)dl * (PW * 2);
;             u32x4 pk[4], pv[4];
;             { const size_t ro = (size_t)(dl * (i0 - 64 + 32 * kt0) + r) * (PW * 2); gload32(pk, kbase + ro, pitch, lane); gload32(pv, vbase + ro, pitch, lane); }
.LBB0_261:
	v_writelane_b32 v255, s0, 36
	s_lshl_b32 s0, s0, 5
	s_add_i32 s0, s0, s17
	s_mul_hi_i32 s2, s0, 0x2aaaaaab
	v_mov_b32_e32 v2, v225
	s_lshr_b32 s3, s2, 31
	s_ashr_i32 s2, s2, 2
	s_add_i32 s2, s2, s3
	v_readfirstlane_b32 s1, v2
	s_ashr_i32 s1, s1, 6
	s_mul_i32 s3, s2, 24
	s_sub_i32 s6, s0, s3
	s_lshl_b32 s3, s1, 14
	s_add_i32 s8, s3, 0
	s_ashr_i32 s3, s2, 31
	s_ashr_i32 s0, s6, 2
	s_lshl_b64 s[76:77], s[2:3], 11
	s_mul_hi_i32 s3, s2, 0xa00000
	s_mul_i32 s2, s2, 0xa00000
	s_add_u32 s4, s26, s2
	s_addc_u32 s5, s27, s3
	s_lshl_b32 s2, s0, 6
	s_ashr_i32 s3, s2, 31
	s_lshl_b64 s[2:3], s[2:3], 1
	s_add_u32 s4, s4, s2
	s_addc_u32 s5, s5, s3
	s_add_u32 s98, s4, 0x300
	s_addc_u32 s99, s5, 0
	v_writelane_b32 v255, s98, 38
	v_writelane_b32 v255, s99, 39
	s_lshl_b32 s83, s1, 1
	s_lshl_b32 s1, s6, 9
	s_and_b32 s1, s1, 0x600
	v_and_b32_e32 v3, 63, v2
	v_bfe_u32 v4, v2, 5, 1
	s_add_u32 s6, s26, s2
	s_addc_u32 s7, s27, s3
	v_lshlrev_b32_e32 v0, 4, v4
	v_mov_b32_e32 v1, v155
	v_lshlrev_b32_e32 v5, 4, v3
	s_waitcnt vmcnt(17)
	v_lshl_add_u64 v[112:113], s[6:7], 0, v[0:1]
	v_bfe_u32 v125, v2, 3, 3
	v_and_b32_e32 v147, 7, v3
	v_bfe_u32 v146, v3, 4, 2
	v_xor_b32_e32 v146, v146, v147
	v_lshlrev_b32_e32 v146, 4, v146
	v_lshlrev_b32_e32 v147, 4, v147
	v_and_b32_e32 v0, 0x70, v5
	v_lshl_add_u64 v[114:115], s[4:5], 0, v[0:1]
	v_or_b32_e32 v1, 8, v125
	v_or_b32_e32 v6, 24, v125
	v_lshrrev_b32_e32 v9, 1, v1
	v_lshrrev_b32_e32 v10, 1, v6
	v_and_b32_e32 v124, 31, v2
	v_xor_b32_e32 v9, v9, v2
	v_xor_b32_e32 v10, v10, v2
	v_lshrrev_b32_e32 v11, 1, v2
	v_bfe_u32 v12, v2, 1, 3
	v_lshlrev_b32_e32 v13, 7, v2
	v_lshrrev_b32_e32 v16, 2, v2
	v_and_b32_e32 v17, 16, v2
	v_lshlrev_b32_e32 v2, 2, v2
	v_writelane_b32 v255, s1, 37
	s_movk_i32 s1, 0x70
	v_and_b32_e32 v18, 4, v125
	v_and_or_b32 v2, v2, 12, v17
	v_bitop3_b32 v8, v5, s1, v3 bitop3:0x48
	v_and_b32_e32 v5, 0x380, v5
	v_and_b32_e32 v13, 0xf80, v13
	v_and_or_b32 v16, v16, 3, v18
	v_lshlrev_b32_e32 v17, 1, v2
	v_or_b32_e32 v2, 1, v18
	v_lshl_add_u32 v7, v125, 7, s8
	v_lshl_add_u32 v1, v1, 7, s8
	v_lshl_add_u32 v6, v6, 7, s8
	v_add_u32_e32 v5, s8, v5
	v_add_u32_e32 v13, s8, v13
	v_lshl_add_u32 v16, v16, 7, s8
	v_cmp_ge_u32_e64 s[8:9], v2, v124
	v_or_b32_e32 v2, 2, v18
	v_cmp_ge_u32_e64 s[12:13], v2, v124
	v_cmp_le_u32_e64 s[14:15], v2, v124
	v_or_b32_e32 v2, 3, v125
	v_cmp_ge_u32_e64 s[16:17], v2, v124
	v_cmp_le_u32_e64 s[18:19], v2, v124
	v_or_b32_e32 v2, 8, v18
	v_cmp_ge_u32_e64 s[20:21], v2, v124
	v_cmp_le_u32_e64 s[22:23], v2, v124
	v_or_b32_e32 v2, 9, v18
	v_cmp_ge_u32_e64 s[24:25], v2, v124
	v_cmp_le_u32_e64 s[26:27], v2, v124
	v_or_b32_e32 v2, 10, v18
	v_cmp_ge_u32_e64 s[28:29], v2, v124
	v_cmp_le_u32_e64 s[30:31], v2, v124
	v_or_b32_e32 v2, 11, v125
	v_cmp_ge_u32_e64 s[34:35], v2, v124
	v_cmp_le_u32_e64 s[36:37], v2, v124
	v_or_b32_e32 v2, 16, v18
	v_cmp_ge_u32_e64 s[38:39], v2, v124
	v_cmp_le_u32_e64 s[40:41], v2, v124
	v_or_b32_e32 v2, 17, v18
	v_cmp_ge_u32_e64 s[42:43], v2, v124
	v_cmp_le_u32_e64 s[44:45], v2, v124
	v_or_b32_e32 v2, 18, v18
	v_readlane_b32 s1, v255, 27
	v_cmp_ge_u32_e64 s[46:47], v2, v124
	v_cmp_le_u32_e64 s[48:49], v2, v124
	v_or_b32_e32 v2, 19, v125
	s_add_u32 s94, s1, s2
	v_readlane_b32 s1, v255, 28
	v_cmp_ge_u32_e64 s[50:51], v2, v124
	v_cmp_le_u32_e64 s[52:53], v2, v124
	v_or_b32_e32 v2, 24, v18
	s_addc_u32 s95, s1, s3
	v_readlane_b32 s1, v255, 31
	v_cmp_ge_u32_e64 s[54:55], v2, v124
	v_cmp_le_u32_e64 s[56:57], v2, v124
	v_or_b32_e32 v2, 25, v18
	s_add_u32 s2, s1, s2
	v_readlane_b32 s1, v255, 32
	v_cmp_ge_u32_e64 s[58:59], v2, v124
	v_cmp_le_u32_e64 s[60:61], v2, v124
	v_or_b32_e32 v2, 26, v18
	s_addc_u32 s3, s1, s3
	s_ashr_i32 s1, s0, 31
	v_lshlrev_b32_e32 v9, 4, v9
	v_lshlrev_b32_e32 v10, 4, v10
	v_bitop3_b32 v11, v4, v11, 7 bitop3:0x78
	v_bitop3_b32 v14, v4, v12, 2 bitop3:0x36
	v_bitop3_b32 v15, v4, v12, 4 bitop3:0x36
	v_bitop3_b32 v12, v4, v12, 6 bitop3:0x36
	v_cmp_ge_u32_e64 s[62:63], v2, v124
	v_cmp_le_u32_e64 s[64:65], v2, v124
	v_or_b32_e32 v2, 27, v125
	s_lshl_b64 s[0:1], s[0:1], 2
	v_readlane_b32 s33, v255, 29
	v_lshlrev_b32_e32 v154, 3, v4
	v_and_b32_e32 v9, 0x70, v9
	v_and_b32_e32 v10, 0x70, v10
	v_lshlrev_b32_e32 v11, 4, v11
	v_lshlrev_b32_e32 v14, 4, v14
	v_lshlrev_b32_e32 v15, 4, v15
	v_lshlrev_b32_e32 v12, 4, v12
	v_cmp_ge_u32_e64 s[66:67], v2, v124
	v_cmp_le_u32_e64 s[68:69], v2, v124
	v_lshlrev_b32_e32 v2, 2, v4
	s_add_u32 s88, s33, s0
	v_readlane_b32 s0, v255, 30
	v_cmp_ge_u32_e64 s[4:5], v18, v124
	v_cmp_le_u32_e64 s[6:7], v18, v124
	v_cmp_lt_u32_e64 s[10:11], v18, v124
	s_waitcnt vmcnt(16)
	v_lshl_add_u64 v[116:117], s[94:95], 0, v[154:155]
	s_addc_u32 s89, s0, s1
	v_cmp_gt_u32_e64 s[70:71], 32, v3
	v_lshl_add_u64 v[118:119], s[2:3], 0, v[154:155]
	v_add_u32_e32 v126, v7, v8
	v_add_u32_e32 v127, v1, v9
	v_add_u32_e32 v128, v6, v10
	v_add_u32_e32 v129, v5, v0
	v_add_u32_e32 v130, v13, v11
	v_add_u32_e32 v131, v13, v14
	v_add_u32_e32 v132, v13, v15
	v_add_u32_e32 v133, v13, v12
	v_add_u32_e32 v134, v16, v17
	v_lshlrev_b32_e32 v154, 1, v2
	s_mov_b32 s82, 0
	s_branch .LBB0_263

; __device__ __forceinline__ void attnA_unit(const Args& a, int unit, LAS unsigned char* lds) {
;     ...
;         const int dl = (pidx == 0) ? 1 : (pidx == 1 ? 4 : 16), Ls = SEQ / dl;
;         if (pidx == 2) { __syncthreads(); }
; #pragma unroll 1
;         for (int e = 0; e < 2; ++e) {
;             const int qt = 2 * wid + e, r = qt % dl, i0 = (512 * blk) / dl + 32 * (qt / dl);
;             const int tq = dl * (i0 + ql) + r;
;             bf16x8 qf[4];
;             { const bf16_t* qp = P + ((size_t)b * SEQ + tq) * PW + 64 * hh + 8 * h;
; #pragma unroll
;               for (int s = 0; s < 4; ++s) qf[s] = *(const bf16x8*)(qp + 16 * s); }
;             f32x16 o0, o1;
; #pragma unroll
;             for (int i = 0; i < 16; ++i) { o0[i] = 0.f; o1[i] = 0.f; }
;             float m = -1e30f, l = 0.f;
;             int kt0 = 0, kt1 = 4;
;             if (i0 - 64 < 0) kt0 = (i0 - 32 < 0) ? 2 : 1;
;             if (i0 + 64 >= Ls) kt1 = (i0 + 32 >= Ls) ? 2 : 3;
;             const unsigned pitch = (unsigned)dl * (PW * 2);
;             u32x4 pk[4], pv[4];
;             { const size_t ro = (size_t)(dl * (i0 - 64 + 32 * kt0) + r) * (PW * 2); gload32(pk, kbase + ro, pitch, lane); gload32(pv, vbase + ro, pitch, lane); }
.LBB0_265:
	s_cmp_eq_u32 s82, 1
	s_mov_b32 s2, 0x14000
	s_cselect_b32 s0, 4, 16
	s_cselect_b32 s1, 2, 4
	s_cselect_b32 s2, 0x5000, s2
	s_cmp_eq_u32 s82, 0
	s_cselect_b32 s72, 1, s0
	v_cvt_f32_ubyte0_e32 v0, s72
	v_rcp_iflag_f32_e32 v2, v0
	s_cselect_b32 s73, 0, s1
	s_cselect_b32 s0, 0x1400, s2
	s_lshr_b32 s1, 0x800, s73
	v_mul_f32_e32 v2, 0x4f7ffffe, v2
	v_cvt_u32_f32_e32 v2, v2
	s_sub_i32 s97, s1, 64
	s_sub_i32 s33, s1, 32
	v_mul_u32_u24_e32 v0, s0, v125
	v_add_u32_e32 v143, v0, v146
	v_xor_b32_e32 v144, 64, v143
	v_add_u32_e32 v145, v0, v147
	s_lshl_b32 s92, s0, 3
	v_readlane_b32 s0, v253, 6
	v_readlane_b32 s1, v253, 7
	v_readlane_b32 s2, v255, 37
	s_mov_b32 s3, s1
	s_sub_i32 s0, 0, s72
	v_readfirstlane_b32 s1, v2
	s_lshr_b32 s96, s2, s73
	s_lshl_b32 s2, s82, 16
	s_mul_i32 s0, s0, s1
	v_mov_b32_e32 v1, v155
	s_mul_hi_u32 s0, s1, s0
	v_writelane_b32 v253, s2, 6
	s_mov_b32 s74, 0
	s_add_i32 s84, s1, s0
	v_lshl_add_u64 v[120:121], v[114:115], 0, v[0:1]
	v_writelane_b32 v253, s3, 7
	s_mov_b32 s93, s3
	s_sub_i32 s85, s96, 32
	s_mov_b64 s[0:1], -1
	s_branch .LBB0_267

; __device__ __forceinline__ void attnA_unit(const Args& a, int unit, LAS unsigned char* lds) {
;     ...
;             const int qt = 2 * wid + e, r = qt % dl, i0 = (512 * blk) / dl + 32 * (qt / dl);
;             const int tq = dl * (i0 + ql) + r;
;             bf16x8 qf[4];
;             { const bf16_t* qp = P + ((size_t)b * SEQ + tq) * PW + 64 * hh + 8 * h;
; #pragma unroll
;               for (int s = 0; s < 4; ++s) qf[s] = *(const bf16x8*)(qp + 16 * s); }
;             f32x16 o0, o1;
; #pragma unroll
;             for (int i = 0; i < 16; ++i) { o0[i] = 0.f; o1[i] = 0.f; }
;             float m = -1e30f, l = 0.f;
;             int kt0 = 0, kt1 = 4;
;             if (i0 - 64 < 0) kt0 = (i0 - 32 < 0) ? 2 : 1;
;             if (i0 + 64 >= Ls) kt1 = (i0 + 32 >= Ls) ? 2 : 3;
;             const unsigned pitch = (unsigned)dl * (PW * 2);
;             u32x4 pk[4], pv[4];
;             { const size_t ro = (size_t)(dl * (i0 - 64 + 32 * kt0) + r) * (PW * 2); gload32(pk, kbase + ro, pitch, lane); gload32(pv, vbase + ro, pitch, lane); }
; #pragma unroll 1
;             for (int kt = kt0; kt <= kt1; ++kt) {
;                 asm volatile("" ::: "memory");
;                 lwrite32<true>(wl, pk, lane); lwrite32<false>(wl + 4096, pv, lane);
;                 if (kt < kt1) { const size_t ro = (size_t)(dl * (i0 - 64 + 32 * (kt + 1)) + r) * (PW * 2); gload32(pk, kbase + ro, pitch, lane); gload32(pv, vbase + ro, pitch, lane); }
;                 asm volatile("s_waitcnt lgkmcnt(0)" ::: "memory");
.LBB0_267:
	s_xor_b64 s[2:3], s[0:1], -1
	s_or_b32 s0, s74, s83
	s_abs_i32 s1, s0
	s_mul_hi_u32 s74, s1, s84
	s_mul_i32 s80, s74, s72
	s_sub_i32 s1, s1, s80
	s_ashr_i32 s75, s0, 31
	s_add_i32 s80, s74, 1
	s_sub_i32 s81, s1, s72
	s_cmp_ge_u32 s1, s72
	s_cselect_b32 s74, s80, s74
	s_cselect_b32 s1, s81, s1
	s_add_i32 s80, s74, 1
	s_cmp_ge_u32 s1, s72
	s_cselect_b32 s1, s80, s74
	s_xor_b32 s80, s1, s75
	s_sub_i32 s1, s80, s75
	s_mul_i32 s74, s1, s72
	s_sub_i32 s74, s0, s74
	s_lshl_b32 s0, s1, 5
	s_add_i32 s81, s0, s96
	v_add_u32_e32 v0, s81, v124
	v_lshlrev_b32_e32 v0, s73, v0
	v_add_u32_e32 v0, s74, v0
	v_ashrrev_i32_e32 v1, 31, v0
	v_lshl_add_u64 v[122:123], s[76:77], 0, v[0:1]
	s_movk_i32 s86, 0x1400
	v_mad_u64_u32 v[0:1], s[0:1], v122, s86, v[112:113]
	s_cmp_lt_i32 s81, 32
	s_cselect_b32 s0, 2, 1
	s_cmp_lt_i32 s81, 64
	v_mad_i32_i24 v1, v123, s86, v1
	s_cselect_b32 s86, s0, 0
	s_lshl_b32 vcc_lo, s86, 5
	s_add_i32 s0, s81, vcc_lo
	s_cmp_lt_i32 s81, s33
	s_cselect_b32 s1, 3, 2
	s_cmp_ge_i32 s81, s97
	s_cselect_b32 s87, s1, 4
	s_sub_i32 s0, s0, 64
	s_lshl_b32 s0, s0, s73
	s_add_i32 s0, s0, s74
	global_load_dwordx4 v[48:51], v[0:1], off
	global_load_dwordx4 v[52:55], v[0:1], off offset:32
	global_load_dwordx4 v[56:59], v[0:1], off offset:64
	global_load_dwordx4 v[60:63], v[0:1], off offset:96
	s_mov_b32 s1, 0xffffdfff
	v_and_b32_e32 v130, s1, v130
	v_and_b32_e32 v131, s1, v131
	v_and_b32_e32 v132, s1, v132
	v_and_b32_e32 v133, s1, v133
	v_and_b32_e32 v134, s1, v134
	s_lshl_b32 s32, s83, 13
	s_mul_i32 s1, s0, 0x1400
	v_readlane_b32 s98, v255, 38
	v_readlane_b32 s99, v255, 39
	s_add_u32 s98, s98, s1
	s_addc_u32 s99, s99, 0
	s_sub_i32 s1, s92, 0x400
	s_mov_b32 m0, s32
	s_nop 0
	global_load_lds_dwordx4 v143, s[98:99]
	s_add_u32 s98, s98, s1
	s_addc_u32 s99, s99, 0
	global_load_lds_dwordx4 v144, s[98:99] offset:1024
	s_add_u32 s98, s98, s1
	s_addc_u32 s99, s99, 0
	global_load_lds_dwordx4 v143, s[98:99] offset:2048
	s_add_u32 s98, s98, s1
	s_addc_u32 s99, s99, 0
	global_load_lds_dwordx4 v144, s[98:99] offset:3072
	s_add_u32 s98, s98, 0x300
	s_addc_u32 s99, s99, 0
	s_add_i32 m0, s32, 0x1000
	s_nop 0
	global_load_lds_dwordx4 v145, s[98:99] offset:3072
	s_sub_u32 s98, s98, s1
	s_subb_u32 s99, s99, 0
	global_load_lds_dwordx4 v145, s[98:99] offset:2048
	s_sub_u32 s98, s98, s1
	s_subb_u32 s99, s99, 0
	global_load_lds_dwordx4 v145, s[98:99] offset:1024
	s_sub_u32 s98, s98, s1
	s_subb_u32 s99, s99, 0
	global_load_lds_dwordx4 v145, s[98:99]
	s_xor_b32 s32, s32, 0x2000
	s_lshl_b32 s1, 32, s73
	s_add_i32 s0, s0, s1
	s_mul_i32 s1, s0, 0x1400
	v_readlane_b32 s98, v255, 38
	v_readlane_b32 s99, v255, 39
	s_add_u32 s98, s98, s1
	s_addc_u32 s99, s99, 0
	s_sub_i32 s1, s92, 0x400
	s_mov_b32 m0, s32
	s_nop 0
	global_load_lds_dwordx4 v143, s[98:99]
	s_add_u32 s98, s98, s1
	s_addc_u32 s99, s99, 0
	global_load_lds_dwordx4 v144, s[98:99] offset:1024
	s_add_u32 s98, s98, s1
	s_addc_u32 s99, s99, 0
	global_load_lds_dwordx4 v143, s[98:99] offset:2048
	s_add_u32 s98, s98, s1
	s_addc_u32 s99, s99, 0
	global_load_lds_dwordx4 v144, s[98:99] offset:3072
	s_add_u32 s98, s98, 0x300
	s_addc_u32 s99, s99, 0
	s_add_i32 m0, s32, 0x1000
	s_nop 0
	global_load_lds_dwordx4 v145, s[98:99] offset:3072
	s_sub_u32 s98, s98, s1
	s_subb_u32 s99, s99, 0
	global_load_lds_dwordx4 v145, s[98:99] offset:2048
	s_sub_u32 s98, s98, s1
	s_subb_u32 s99, s99, 0
	global_load_lds_dwordx4 v145, s[98:99] offset:1024
	s_sub_u32 s98, s98, s1
	s_subb_u32 s99, s99, 0
	global_load_lds_dwordx4 v145, s[98:99]
	s_xor_b32 s32, s32, 0x2000
	s_add_i32 s0, s85, vcc_lo
	s_lshl_b32 s1, s80, 5
	s_add_i32 s0, s0, s1
	s_lshl_b32 s1, s75, 5
	v_mov_b32_e32 v135, 0
	s_sub_i32 s75, s0, s1
	v_mov_b32_e32 v136, 0xf149f2ca
	v_mov_b32_e32 v16, 0
	v_mov_b32_e32 v17, v135
	v_mov_b32_e32 v18, v135
	v_mov_b32_e32 v19, v135
	v_mov_b32_e32 v20, v135
	v_mov_b32_e32 v21, v135
	v_mov_b32_e32 v22, v135
	v_mov_b32_e32 v23, v135
	v_mov_b32_e32 v24, v135
	v_mov_b32_e32 v25, v135
	v_mov_b32_e32 v26, v135
	v_mov_b32_e32 v27, v135
	v_mov_b32_e32 v28, v135
	v_mov_b32_e32 v29, v135
	v_mov_b32_e32 v30, v135
	v_mov_b32_e32 v31, v135
	v_mov_b32_e32 v0, 0
	v_mov_b32_e32 v1, v135
	v_mov_b32_e32 v2, v135
	v_mov_b32_e32 v3, v135
	v_mov_b32_e32 v4, v135
	v_mov_b32_e32 v5, v135
	v_mov_b32_e32 v6, v135
	v_mov_b32_e32 v7, v135
	v_mov_b32_e32 v8, v135
	v_mov_b32_e32 v9, v135
	v_mov_b32_e32 v10, v135
	v_mov_b32_e32 v11, v135
	v_mov_b32_e32 v12, v135
	v_mov_b32_e32 v13, v135
	v_mov_b32_e32 v14, v135
	v_mov_b32_e32 v15, v135
.LBB0_268:
	s_cmp_ge_u32 s86, s87
	s_cselect_b64 s[80:81], -1, 0
	s_and_b64 vcc, exec, s[80:81]
	s_cbranch_vccnz .LaD_w0
	s_waitcnt vmcnt(8)
	s_branch .LBB0_270

; #define LAS __attribute__((address_space(3)))
; template <bool KLDS>
; __device__ __forceinline__ void attn_step(const bf16x8 (&kf)[4], LAS const unsigned char* kb, const bf16x8 (&vf)[2][2], const bf16x8 (&qf)[4], f32x16& o0, f32x16& o1, float& m, float& l, int lane, int maskmode) {
;     ...
; #pragma unroll
;     for (int s = 0; s < 4; ++s) {
;         if (KLDS) { const int pc = (2 * s + h) ^ ((ql >> 1) & 7); const bf16x8 k1 = *(const LAS bf16x8*)(kb + ql * 128 + pc * 16); S = __builtin_amdgcn_mfma_f32_32x32x16_bf16(k1, qf[s], S, 0, 0, 0); }
;         else S = __builtin_amdgcn_mfma_f32_32x32x16_bf16(kf[s], qf[s], S, 0, 0, 0);
;     }
; __device__ __forceinline__ void attnA_unit(const Args& a, int unit, LAS unsigned char* lds) {
;     ...
;                 lwrite32<true>(wl, pk, lane); lwrite32<false>(wl + 4096, pv, lane);
;                 if (kt < kt1) { const size_t ro = (size_t)(dl * (i0 - 64 + 32 * (kt + 1)) + r) * (PW * 2); gload32(pk, kbase + ro, pitch, lane); gload32(pv, vbase + ro, pitch, lane); }
;                 asm volatile("s_waitcnt lgkmcnt(0)" ::: "memory");
;                 bf16x8 kf[4], vf[2][2];
;                 load_kf(wl, kf, lane); load_vf(wl + 4096, vf, lane);
.LBB0_270:
	s_waitcnt lgkmcnt(0)
	ds_read_b128 v[32:35], v130
	ds_read_b128 v[96:99], v131
	s_cmp_lt_i32 s86, 4
	s_waitcnt lgkmcnt(1)
	v_mfma_f32_32x32x16_bf16 v[32:47], v[32:35], v[48:51], 0
	s_waitcnt lgkmcnt(0)
	v_mfma_f32_32x32x16_bf16 v[32:47], v[96:99], v[52:55], v[32:47]
	ds_read_b128 v[96:99], v132
	ds_read_b128 v[138:141], v133
	s_waitcnt lgkmcnt(1)
	v_mfma_f32_32x32x16_bf16 v[32:47], v[96:99], v[56:59], v[32:47]
	ds_read_b64_tr_b16 v[108:109], v134 offset:4096
	ds_read_b64_tr_b16 v[110:111], v134 offset:5120
	ds_read_b64_tr_b16 v[106:107], v134 offset:5184
	ds_read_b64_tr_b16 v[104:105], v134 offset:4160
	ds_read_b64_tr_b16 v[100:101], v134 offset:6144
	ds_read_b64_tr_b16 v[102:103], v134 offset:7168
	ds_read_b64_tr_b16 v[98:99], v134 offset:7232
	ds_read_b64_tr_b16 v[96:97], v134 offset:6208
	s_waitcnt lgkmcnt(8)
	v_mfma_f32_32x32x16_bf16 v[32:47], v[138:141], v[60:63], v[32:47]
	v_xor_b32_e32 v130, 0x2000, v130
	v_xor_b32_e32 v131, 0x2000, v131
	v_xor_b32_e32 v132, 0x2000, v132
	v_xor_b32_e32 v133, 0x2000, v133
	v_xor_b32_e32 v134, 0x2000, v134
	s_cbranch_scc1 .LBB0_272
	s_cmp_eq_u32 s86, 4
	s_cselect_b64 s[0:1], -1, 0
	s_cbranch_execz .LBB0_273
	s_branch .LBB0_274

; __device__ __forceinline__ unsigned pk2n(float lo, float hi) { const f32x2v v = {lo, hi}; const bf16v2 b = __builtin_convertvector(v, bf16v2); return __builtin_bit_cast(unsigned, b); }
; __device__ __forceinline__ float fexp2(float x) { return __builtin_amdgcn_exp2f(x); }
; template <bool KLDS>
; __device__ __forceinline__ void attn_step(const bf16x8 (&kf)[4], LAS const unsigned char* kb, const bf16x8 (&vf)[2][2], const bf16x8 (&qf)[4], f32x16& o0, f32x16& o1, float& m, float& l, int lane, int maskmode) {
;     ...
;     float tm = S[0];
; #pragma unroll
;     for (int i = 1; i < 16; ++i) tm = fmaxf(tm, S[i]);
;     tm = fmaxf(tm, __shfl_xor(tm, 32));
;     const float mn = fmaxf(m, tm), al = fexp2(m - mn); m = mn;
;     float ps = 0.f;
; #pragma unroll
;     for (int i = 0; i < 16; ++i) { S[i] = fexp2(S[i] - mn); ps += S[i]; }
;     l = l * al + ps;
; #pragma unroll
;     for (int i = 0; i < 16; ++i) { o0[i] *= al; o1[i] *= al; }
;     bf16x8 pf[2];
; #pragma unroll
;     for (int s2 = 0; s2 < 2; ++s2) {
;         u32x4 w; w.x = pk2n(S[8 * s2 + 0], S[8 * s2 + 1]); w.y = pk2n(S[8 * s2 + 2], S[8 * s2 + 3]); w.z = pk2n(S[8 * s2 + 4], S[8 * s2 + 5]); w.w = pk2n(S[8 * s2 + 6], S[8 * s2 + 7]);
;         pf[s2] = __builtin_bit_cast(bf16x8, w);
;     }
; #pragma unroll
;     for (int s2 = 0; s2 < 2; ++s2) {
;         o0 = __builtin_amdgcn_mfma_f32_32x32x16_bf16(vf[s2][0], pf[s2], o0, 0, 0, 0);
;         o1 = __builtin_amdgcn_mfma_f32_32x32x16_bf16(vf[s2][1], pf[s2], o1, 0, 0, 0);
;     }
; __device__ __forceinline__ void attnA_unit(const Args& a, int unit, LAS unsigned char* lds) {
;     ...
;                 if (kt < kt1) { const size_t ro = (size_t)(dl * (i0 - 64 + 32 * (kt + 1)) + r) * (PW * 2); gload32(pk, kbase + ro, pitch, lane); gload32(pv, vbase + ro, pitch, lane); }
.LBB0_276:
	s_nop 5
	v_max_f32_e32 v137, v33, v33
	v_max_f32_e32 v138, v32, v32
	v_max_f32_e32 v137, v138, v137
	v_max3_f32 v137, v137, v34, v35
	v_max3_f32 v137, v137, v36, v37
	v_max3_f32 v137, v137, v38, v39
	v_max3_f32 v137, v137, v40, v41
	v_max3_f32 v137, v137, v42, v43
	v_max3_f32 v137, v137, v44, v45
	v_max3_f32 v137, v137, v46, v47
	ds_bpermute_b32 v138, v248, v137
	s_add_i32 s86, s86, 1
	s_add_i32 s75, s75, 32
	s_and_b64 vcc, exec, s[80:81]
	s_waitcnt lgkmcnt(0)
	s_cmp_lt_u32 s86, s87
	s_cbranch_scc0 .LaD_ni
	s_lshl_b32 s0, s75, s73
	s_add_i32 s0, s0, s74
	s_mul_i32 s1, s0, 0x1400
	v_readlane_b32 s98, v255, 38
	v_readlane_b32 s99, v255, 39
	s_add_u32 s98, s98, s1
	s_addc_u32 s99, s99, 0
	s_sub_i32 s1, s92, 0x400
	s_mov_b32 m0, s32
	s_nop 0
	global_load_lds_dwordx4 v143, s[98:99]
	s_add_u32 s98, s98, s1
	s_addc_u32 s99, s99, 0
	global_load_lds_dwordx4 v144, s[98:99] offset:1024
	s_add_u32 s98, s98, s1
	s_addc_u32 s99, s99, 0
	global_load_lds_dwordx4 v143, s[98:99] offset:2048
	s_add_u32 s98, s98, s1
	s_addc_u32 s99, s99, 0
	global_load_lds_dwordx4 v144, s[98:99] offset:3072
	s_add_u32 s98, s98, 0x300
	s_addc_u32 s99, s99, 0
	s_add_i32 m0, s32, 0x1000
	s_nop 0
	global_load_lds_dwordx4 v145, s[98:99] offset:3072
	s_sub_u32 s98, s98, s1
	s_subb_u32 s99, s99, 0
	global_load_lds_dwordx4 v145, s[98:99] offset:2048
	s_sub_u32 s98, s98, s1
	s_subb_u32 s99, s99, 0
	global_load_lds_dwordx4 v145, s[98:99] offset:1024
	s_sub_u32 s98, s98, s1
	s_subb_u32 s99, s99, 0
	global_load_lds_dwordx4 v145, s[98:99]
	s_xor_b32 s32, s32, 0x2000
.LaD_ni:
	v_max3_f32 v137, v136, v137, v138
	v_sub_f32_e32 v32, v32, v137
	v_exp_f32_e32 v138, v32
	v_sub_f32_e32 v33, v33, v137
	v_exp_f32_e32 v33, v33
	v_sub_f32_e32 v34, v34, v137
	v_exp_f32_e32 v139, v34
	v_sub_f32_e32 v34, v35, v137
	v_exp_f32_e32 v35, v34
	v_sub_f32_e32 v34, v36, v137
	v_add_f32_e32 v32, 0, v138
	v_exp_f32_e32 v36, v34
	v_sub_f32_e32 v34, v37, v137
	v_add_f32_e32 v32, v33, v32
	v_exp_f32_e32 v37, v34
	v_sub_f32_e32 v34, v38, v137
	v_add_f32_e32 v32, v139, v32
	v_exp_f32_e32 v38, v34
	v_sub_f32_e32 v34, v39, v137
	v_add_f32_e32 v32, v35, v32
	v_exp_f32_e32 v39, v34
	v_sub_f32_e32 v34, v40, v137
	v_add_f32_e32 v32, v36, v32
	v_exp_f32_e32 v40, v34
	v_sub_f32_e32 v34, v41, v137
	v_add_f32_e32 v32, v37, v32
	v_exp_f32_e32 v41, v34
	v_sub_f32_e32 v34, v42, v137
	v_add_f32_e32 v32, v38, v32
	v_exp_f32_e32 v42, v34
	v_sub_f32_e32 v34, v43, v137
	v_add_f32_e32 v32, v39, v32
	v_exp_f32_e32 v43, v34
	v_sub_f32_e32 v34, v44, v137
	v_add_f32_e32 v32, v40, v32
	v_exp_f32_e32 v44, v34
	v_sub_f32_e32 v34, v45, v137
	v_add_f32_e32 v32, v41, v32
	v_exp_f32_e32 v45, v34
	v_sub_f32_e32 v34, v46, v137
	v_add_f32_e32 v32, v42, v32
	v_exp_f32_e32 v46, v34
	v_sub_f32_e32 v34, v47, v137
	v_sub_f32_e32 v136, v136, v137
	v_add_f32_e32 v32, v43, v32
	v_exp_f32_e32 v47, v34
	v_add_f32_e32 v32, v44, v32
	v_exp_f32_e32 v34, v136
	v_add_f32_e32 v32, v45, v32
	v_add_f32_e32 v32, v46, v32
	v_add_f32_e32 v32, v47, v32
	v_fmac_f32_e32 v32, v135, v34
	v_pk_mul_f32 v[30:31], v[30:31], v[34:35] op_sel_hi:[1,0]
	v_pk_mul_f32 v[28:29], v[28:29], v[34:35] op_sel_hi:[1,0]
	v_pk_mul_f32 v[26:27], v[26:27], v[34:35] op_sel_hi:[1,0]
	v_pk_mul_f32 v[24:25], v[24:25], v[34:35] op_sel_hi:[1,0]
	v_pk_mul_f32 v[22:23], v[22:23], v[34:35] op_sel_hi:[1,0]
	v_pk_mul_f32 v[20:21], v[20:21], v[34:35] op_sel_hi:[1,0]
	v_pk_mul_f32 v[18:19], v[18:19], v[34:35] op_sel_hi:[1,0]
	v_pk_mul_f32 v[16:17], v[16:17], v[34:35] op_sel_hi:[1,0]
	v_pk_mul_f32 v[14:15], v[14:15], v[34:35] op_sel_hi:[1,0]
	v_pk_mul_f32 v[12:13], v[12:13], v[34:35] op_sel_hi:[1,0]
	v_pk_mul_f32 v[10:11], v[10:11], v[34:35] op_sel_hi:[1,0]
	v_pk_mul_f32 v[8:9], v[8:9], v[34:35] op_sel_hi:[1,0]
	v_pk_mul_f32 v[6:7], v[6:7], v[34:35] op_sel_hi:[1,0]
	v_pk_mul_f32 v[4:5], v[4:5], v[34:35] op_sel_hi:[1,0]
	v_pk_mul_f32 v[2:3], v[2:3], v[34:35] op_sel_hi:[1,0]
	v_pk_mul_f32 v[0:1], v[0:1], v[34:35] op_sel_hi:[1,0]
	v_cvt_pk_bf16_f32 v34, v138, v33
	v_cvt_pk_bf16_f32 v35, v139, v35
	v_cvt_pk_bf16_f32 v36, v36, v37
	v_cvt_pk_bf16_f32 v37, v38, v39
	v_cvt_pk_bf16_f32 v38, v40, v41
	v_cvt_pk_bf16_f32 v39, v42, v43
	v_mfma_f32_32x32x16_bf16 v[16:31], v[108:111], v[34:37], v[16:31]
	v_cvt_pk_bf16_f32 v40, v44, v45
	v_cvt_pk_bf16_f32 v41, v46, v47
	v_mfma_f32_32x32x16_bf16 v[0:15], v[104:107], v[34:37], v[0:15]
	s_nop 0
	v_mfma_f32_32x32x16_bf16 v[16:31], v[100:103], v[38:41], v[16:31]
	v_mfma_f32_32x32x16_bf16 v[0:15], v[96:99], v[38:41], v[0:15]
	s_cbranch_vccnz .LBB0_278
	v_mov_b32_e32 v136, v137
	v_mov_b32_e32 v135, v32
	s_branch .LBB0_268
